# window FAST steps: running max folded into the MFMA accumulator init (16 fewer f32 subs per step), on top of the batched/relaxed NSA loops
# baseline (speedup 1.0000x reference)
.LBB0_1024:
	s_and_b64 vcc, exec, s[4:5]
	s_cbranch_vccz .LBB0_1014
	ds_read_b128 v[160:163], v118
	ds_read_b128 v[164:167], v118 offset:64
	ds_read_b128 v[168:171], v118 offset:2304
	ds_read_b128 v[172:175], v118 offset:2368
	ds_read_b128 v[176:179], v118 offset:4608
	ds_read_b128 v[180:183], v118 offset:4672
	ds_read_b128 v[184:187], v118 offset:6912
	ds_read_b128 v[188:191], v118 offset:6976
	v_add_u32_e32 v0, s43, v120
	v_cvt_f32_i32_e32 v2, v0
	s_mov_b32 s4, 2.0
	s_mov_b32 s5, 0x40400000
	v_fma_f32 v0, -v96, v2, -v126
	v_mov_b32_e32 v76, v0
	v_fma_f32 v77, -v96, v2, v96
	v_sub_f32_e32 v77, v77, v126
	v_fmac_f32_e32 v76, 0, v96
	v_pk_fma_f32 v[78:79], v[96:97], s[4:5], v[0:1] op_sel_hi:[1,1,0]
	s_mov_b32 s4, 0x41800000
	s_mov_b32 s5, 0x41880000
	s_waitcnt lgkmcnt(7)
	v_mfma_f32_16x16x32_bf16 v[76:79], v[160:163], v[4:7], v[76:79]
	v_pk_fma_f32 v[82:83], v[108:109], s[90:91], v[0:1] op_sel_hi:[1,1,0]
	v_pk_fma_f32 v[80:81], v[106:107], s[4:5], v[0:1] op_sel_hi:[1,1,0]
	v_pk_fma_f32 v[130:131], v[108:109], s[92:93], v[0:1] op_sel_hi:[1,1,0]
	s_waitcnt lgkmcnt(6)
	v_mfma_f32_16x16x32_bf16 v[88:91], v[164:167], v[8:11], v[76:79]
	ds_read_b128 v[196:199], v243
	ds_read_b128 v[200:203], v243 offset:64
	s_nop 2
	v_pk_fma_f32 v[128:129], v[106:107], s[34:35], v[0:1] op_sel_hi:[1,1,0]
	v_pk_fma_f32 v[134:135], v[108:109], s[22:23], v[0:1] op_sel_hi:[1,1,0]
	s_waitcnt lgkmcnt(7)
	v_mfma_f32_16x16x32_bf16 v[76:79], v[168:171], v[4:7], v[80:83]
	s_nop 2
	v_pk_fma_f32 v[132:133], v[106:107], s[72:73], v[0:1] op_sel_hi:[1,1,0]
	v_max3_f32 v0, v88, s36, v89
	s_waitcnt lgkmcnt(6)
	v_mfma_f32_16x16x32_bf16 v[84:87], v[172:175], v[8:11], v[76:79]
	ds_read_b128 v[204:207], v243 offset:2304
	ds_read_b128 v[208:211], v243 offset:2368
	s_nop 2
	v_max3_f32 v0, v0, v90, v91
	s_waitcnt lgkmcnt(7)
	v_mfma_f32_16x16x32_bf16 v[76:79], v[176:179], v[4:7], v[128:131]
	s_nop 2
	v_max3_f32 v0, v0, v84, v85
	v_max3_f32 v0, v0, v86, v87
	s_waitcnt lgkmcnt(6)
	v_mfma_f32_16x16x32_bf16 v[76:79], v[180:183], v[8:11], v[76:79]
	ds_read_b128 v[212:215], v243 offset:4608
	ds_read_b128 v[216:219], v243 offset:4672
	s_waitcnt lgkmcnt(7)
	v_mfma_f32_16x16x32_bf16 v[80:83], v[184:187], v[4:7], v[132:135]
	s_nop 4
	v_max3_f32 v0, v0, v76, v77
	v_max3_f32 v0, v0, v78, v79
	s_waitcnt lgkmcnt(6)
	v_mfma_f32_16x16x32_bf16 v[80:83], v[188:191], v[8:11], v[80:83]
	ds_read_b128 v[220:223], v243 offset:6912
	ds_read_b128 v[224:227], v243 offset:6976
	s_nop 7
	v_max3_f32 v0, v0, v80, v81
	v_max3_f32 v0, v0, v82, v83
	v_cmp_lt_f32_e32 vcc, 0, v0
	s_cbranch_vccz .LBB0_1027
	ds_bpermute_b32 v2, v115, v0
	v_max_f32_e32 v0, v0, v0
	s_waitcnt lgkmcnt(0)
	v_max_f32_e32 v2, v2, v2
	v_max_f32_e32 v0, v0, v2
	ds_bpermute_b32 v2, v114, v0
	s_waitcnt lgkmcnt(0)
	v_max3_f32 v2, 0, v0, v2
	v_sub_f32_e32 v0, 0, v2
	v_exp_f32_e32 v0, v0
	v_add_f32_e32 v126, v126, v2
	v_mul_f32_e32 v127, v127, v0
	v_pk_mul_f32 v[62:63], v[62:63], v[0:1] op_sel_hi:[1,0]
	v_pk_mul_f32 v[60:61], v[60:61], v[0:1] op_sel_hi:[1,0]
	v_pk_mul_f32 v[66:67], v[66:67], v[0:1] op_sel_hi:[1,0]
	v_pk_mul_f32 v[64:65], v[64:65], v[0:1] op_sel_hi:[1,0]
	v_pk_mul_f32 v[70:71], v[70:71], v[0:1] op_sel_hi:[1,0]
	v_pk_mul_f32 v[68:69], v[68:69], v[0:1] op_sel_hi:[1,0]
	v_pk_mul_f32 v[74:75], v[74:75], v[0:1] op_sel_hi:[1,0]
	v_pk_mul_f32 v[72:73], v[72:73], v[0:1] op_sel_hi:[1,0]
	v_sub_f32_e32 v88, v88, v2
	v_sub_f32_e32 v89, v89, v2
	v_sub_f32_e32 v90, v90, v2
	v_sub_f32_e32 v91, v91, v2
	v_sub_f32_e32 v84, v84, v2
	v_sub_f32_e32 v85, v85, v2
	v_sub_f32_e32 v86, v86, v2
	v_sub_f32_e32 v87, v87, v2
	v_sub_f32_e32 v76, v76, v2
	v_sub_f32_e32 v77, v77, v2
	v_sub_f32_e32 v78, v78, v2
	v_sub_f32_e32 v79, v79, v2
	v_sub_f32_e32 v80, v80, v2
	v_sub_f32_e32 v81, v81, v2
	v_sub_f32_e32 v82, v82, v2
	v_sub_f32_e32 v83, v83, v2
.LBB0_1027:
	v_exp_f32_e32 v0, v88
	v_exp_f32_e32 v3, v89
	v_exp_f32_e32 v88, v90
	v_exp_f32_e32 v89, v91
	v_add_f32_e32 v2, 0, v0
	v_exp_f32_e32 v84, v84
	v_add_f32_e32 v2, v3, v2
	v_exp_f32_e32 v85, v85
	v_add_f32_e32 v2, v88, v2
	v_exp_f32_e32 v86, v86
	v_add_f32_e32 v2, v89, v2
	v_exp_f32_e32 v87, v87
	v_cvt_pk_bf16_f32 v128, v0, v3
	v_add_f32_e32 v2, v84, v2
	v_exp_f32_e32 v0, v76
	v_add_f32_e32 v2, v85, v2
	v_exp_f32_e32 v3, v77
	v_add_f32_e32 v2, v86, v2
	v_exp_f32_e32 v76, v78
	v_add_f32_e32 v2, v87, v2
	v_exp_f32_e32 v77, v79
	v_add_f32_e32 v2, v0, v2
	v_exp_f32_e32 v78, v80
	v_add_f32_e32 v2, v3, v2
	v_exp_f32_e32 v79, v81
	v_add_f32_e32 v2, v76, v2
	v_add_f32_e32 v2, v77, v2
	v_add_f32_e32 v2, v78, v2
	v_cvt_pk_bf16_f32 v129, v88, v89
	v_add_f32_e32 v2, v79, v2
	v_cvt_pk_bf16_f32 v89, v76, v77
	v_cvt_pk_bf16_f32 v90, v78, v79
	v_cvt_pk_bf16_f32 v130, v84, v85
	v_cvt_pk_bf16_f32 v131, v86, v87
	s_waitcnt lgkmcnt(0)
	s_waitcnt lgkmcnt(0)
	v_mfma_f32_16x16x32_bf16 v[60:63], v[196:199], v[128:131], v[60:63]
	v_exp_f32_e32 v80, v82
	v_exp_f32_e32 v81, v83
	v_cvt_pk_bf16_f32 v88, v0, v3
	v_add_u32_e32 v0, 0x800, v123
	v_add_f32_e32 v2, v80, v2
	v_cvt_pk_bf16_f32 v91, v80, v81
	v_add_f32_e32 v2, v81, v2
	v_add_f32_e32 v2, v127, v2
	s_waitcnt lgkmcnt(0)
	v_mfma_f32_16x16x32_bf16 v[76:79], v[200:203], v[88:91], v[60:63]
	s_nop 2
	s_waitcnt lgkmcnt(0)
	v_mfma_f32_16x16x32_bf16 v[60:63], v[204:207], v[128:131], v[64:67]
	s_nop 2
	v_add_u32_e32 v0, 0x1000, v123
	s_waitcnt lgkmcnt(0)
	v_mfma_f32_16x16x32_bf16 v[80:83], v[208:211], v[88:91], v[60:63]
	s_nop 2
	v_add_u32_e32 v0, 0x1800, v123
	s_waitcnt lgkmcnt(1)
	v_mfma_f32_16x16x32_bf16 v[60:63], v[212:215], v[128:131], v[68:71]
	s_waitcnt lgkmcnt(0)
	v_mfma_f32_16x16x32_bf16 v[84:87], v[216:219], v[88:91], v[60:63]
	s_nop 4
	s_waitcnt lgkmcnt(0)
	v_mfma_f32_16x16x32_bf16 v[60:63], v[220:223], v[128:131], v[72:75]
	v_mov_b32_e32 v0, v126
	v_mfma_f32_16x16x32_bf16 v[88:91], v[224:227], v[88:91], v[60:63]
	s_cmp_lt_i32 s17, s11
	s_cselect_b64 s[4:5], -1, 0
	s_cmp_ge_i32 s17, s11
	s_cbranch_scc0 .LBB0_1015
	s_branch .LBB0_1016

.LBB0_1029:
	s_and_b64 vcc, exec, s[4:5]
	s_cbranch_vccz .LBB0_1023
	ds_read_b128 v[160:163], v119
	ds_read_b128 v[164:167], v119 offset:64
	ds_read_b128 v[168:171], v119 offset:2304
	ds_read_b128 v[172:175], v119 offset:2368
	ds_read_b128 v[176:179], v119 offset:4608
	ds_read_b128 v[180:183], v119 offset:4672
	ds_read_b128 v[184:187], v119 offset:6912
	ds_read_b128 v[188:191], v119 offset:6976
	v_or_b32_e32 v3, s1, v98
	v_sub_u32_e32 v3, v103, v3
	v_cvt_f32_i32_e32 v3, v3
	s_mov_b32 s4, 2.0
	s_mov_b32 s5, 0x40400000
	v_fma_f32 v68, -v96, v3, -v0
	v_pk_fma_f32 v[62:63], v[96:97], s[4:5], v[68:69] op_sel_hi:[1,1,0]
	s_mov_b32 s4, 0x41800000
	s_mov_b32 s5, 0x41880000
	v_mov_b32_e32 v60, v68
	v_pk_fma_f32 v[66:67], v[108:109], s[90:91], v[68:69] op_sel_hi:[1,1,0]
	v_pk_fma_f32 v[64:65], v[106:107], s[4:5], v[68:69] op_sel_hi:[1,1,0]
	v_pk_fma_f32 v[128:129], v[108:109], s[92:93], v[68:69] op_sel_hi:[1,1,0]
	v_pk_fma_f32 v[126:127], v[106:107], s[34:35], v[68:69] op_sel_hi:[1,1,0]
	v_pk_fma_f32 v[132:133], v[108:109], s[22:23], v[68:69] op_sel_hi:[1,1,0]
	v_pk_fma_f32 v[130:131], v[106:107], s[72:73], v[68:69] op_sel_hi:[1,1,0]
	v_fma_f32 v61, -v96, v3, v96
	v_sub_f32_e32 v61, v61, v0
	v_fmac_f32_e32 v60, 0, v96
	s_nop 0
	s_waitcnt lgkmcnt(7)
	v_mfma_f32_16x16x32_bf16 v[60:63], v[160:163], v[4:7], v[60:63]
	s_waitcnt lgkmcnt(6)
	v_mfma_f32_16x16x32_bf16 v[72:75], v[164:167], v[8:11], v[60:63]
	ds_read_b128 v[196:199], v244
	ds_read_b128 v[200:203], v244 offset:64
	s_nop 4
	s_nop 1
	v_max3_f32 v3, v72, s36, v73
	s_waitcnt lgkmcnt(7)
	v_mfma_f32_16x16x32_bf16 v[60:63], v[168:171], v[4:7], v[64:67]
	s_nop 2
	v_max3_f32 v3, v3, v74, v75
	s_waitcnt lgkmcnt(6)
	v_mfma_f32_16x16x32_bf16 v[68:71], v[172:175], v[8:11], v[60:63]
	ds_read_b128 v[204:207], v244 offset:2304
	ds_read_b128 v[208:211], v244 offset:2368
	s_nop 2
	s_nop 2
	v_max3_f32 v3, v3, v68, v69
	s_waitcnt lgkmcnt(7)
	v_mfma_f32_16x16x32_bf16 v[60:63], v[176:179], v[4:7], v[126:129]
	s_nop 2
	v_max3_f32 v3, v3, v70, v71
	s_waitcnt lgkmcnt(6)
	v_mfma_f32_16x16x32_bf16 v[60:63], v[180:183], v[8:11], v[60:63]
	ds_read_b128 v[212:215], v244 offset:4608
	ds_read_b128 v[216:219], v244 offset:4672
	s_waitcnt lgkmcnt(7)
	v_mfma_f32_16x16x32_bf16 v[64:67], v[184:187], v[4:7], v[130:133]
	s_nop 4
	v_max3_f32 v3, v3, v60, v61
	v_max3_f32 v3, v3, v62, v63
	s_waitcnt lgkmcnt(6)
	v_mfma_f32_16x16x32_bf16 v[64:67], v[188:191], v[8:11], v[64:67]
	ds_read_b128 v[220:223], v244 offset:6912
	ds_read_b128 v[224:227], v244 offset:6976
	s_nop 7
	v_max3_f32 v3, v3, v64, v65
	v_max3_f32 v3, v3, v66, v67
	v_cmp_lt_f32_e32 vcc, 0, v3
	s_cbranch_vccz .LBB0_1032
	ds_bpermute_b32 v126, v115, v3
	v_max_f32_e32 v3, v3, v3
	s_waitcnt lgkmcnt(0)
	v_max_f32_e32 v126, v126, v126
	v_max_f32_e32 v3, v3, v126
	ds_bpermute_b32 v126, v114, v3
	s_waitcnt lgkmcnt(0)
	v_max3_f32 v3, 0, v3, v126
	v_add_f32_e32 v192, v0, v3
	v_sub_f32_e32 v0, 0, v3
	v_exp_f32_e32 v0, v0
	s_nop 0
	v_mul_f32_e32 v2, v2, v0
	v_pk_mul_f32 v[78:79], v[78:79], v[0:1] op_sel_hi:[1,0]
	v_pk_mul_f32 v[76:77], v[76:77], v[0:1] op_sel_hi:[1,0]
	v_pk_mul_f32 v[82:83], v[82:83], v[0:1] op_sel_hi:[1,0]
	v_pk_mul_f32 v[80:81], v[80:81], v[0:1] op_sel_hi:[1,0]
	v_pk_mul_f32 v[86:87], v[86:87], v[0:1] op_sel_hi:[1,0]
	v_pk_mul_f32 v[84:85], v[84:85], v[0:1] op_sel_hi:[1,0]
	v_pk_mul_f32 v[90:91], v[90:91], v[0:1] op_sel_hi:[1,0]
	v_pk_mul_f32 v[88:89], v[88:89], v[0:1] op_sel_hi:[1,0]
	v_sub_f32_e32 v72, v72, v3
	v_sub_f32_e32 v73, v73, v3
	v_sub_f32_e32 v74, v74, v3
	v_sub_f32_e32 v75, v75, v3
	v_sub_f32_e32 v68, v68, v3
	v_sub_f32_e32 v69, v69, v3
	v_sub_f32_e32 v70, v70, v3
	v_sub_f32_e32 v71, v71, v3
	v_sub_f32_e32 v60, v60, v3
	v_sub_f32_e32 v61, v61, v3
	v_sub_f32_e32 v62, v62, v3
	v_sub_f32_e32 v63, v63, v3
	v_sub_f32_e32 v64, v64, v3
	v_sub_f32_e32 v65, v65, v3
	v_sub_f32_e32 v66, v66, v3
	v_sub_f32_e32 v67, v67, v3
	v_mov_b32_e32 v0, v192
.LBB0_1032:
	v_exp_f32_e32 v3, v72
	v_exp_f32_e32 v73, v73
	v_exp_f32_e32 v74, v74
	v_exp_f32_e32 v75, v75
	v_add_f32_e32 v72, 0, v3
	v_exp_f32_e32 v68, v68
	v_add_f32_e32 v72, v73, v72
	v_exp_f32_e32 v69, v69
	v_add_f32_e32 v72, v74, v72
	v_exp_f32_e32 v70, v70
	v_add_f32_e32 v72, v75, v72
	v_exp_f32_e32 v71, v71
	v_cvt_pk_bf16_f32 v128, v3, v73
	v_add_f32_e32 v72, v68, v72
	v_exp_f32_e32 v3, v60
	v_add_f32_e32 v72, v69, v72
	v_exp_f32_e32 v61, v61
	v_add_f32_e32 v72, v70, v72
	v_exp_f32_e32 v62, v62
	v_add_f32_e32 v72, v71, v72
	v_exp_f32_e32 v63, v63
	v_add_f32_e32 v60, v3, v72
	v_exp_f32_e32 v64, v64
	v_add_f32_e32 v60, v61, v60
	v_exp_f32_e32 v65, v65
	v_add_f32_e32 v60, v62, v60
	v_exp_f32_e32 v66, v66
	v_add_f32_e32 v60, v63, v60
	v_exp_f32_e32 v67, v67
	v_add_f32_e32 v60, v64, v60
	v_add_f32_e32 v60, v65, v60
	v_add_f32_e32 v60, v66, v60
	v_add_f32_e32 v60, v67, v60
	v_cvt_pk_bf16_f32 v72, v3, v61
	v_cvt_pk_bf16_f32 v73, v62, v63
	v_add_f32_e32 v127, v2, v60
	v_cvt_pk_bf16_f32 v129, v74, v75
	v_cvt_pk_bf16_f32 v74, v64, v65
	v_cvt_pk_bf16_f32 v75, v66, v67
	v_cvt_pk_bf16_f32 v130, v68, v69
	v_cvt_pk_bf16_f32 v131, v70, v71
	v_add_u32_e32 v2, 0x800, v124
	s_waitcnt lgkmcnt(2)
	s_waitcnt lgkmcnt(0)
	v_mfma_f32_16x16x32_bf16 v[60:63], v[196:199], v[128:131], v[76:79]
	v_mov_b32_e32 v126, v0
	s_waitcnt lgkmcnt(1)
	v_mfma_f32_16x16x32_bf16 v[60:63], v[200:203], v[72:75], v[60:63]
	v_add_u32_e32 v2, 0x1000, v124
	s_waitcnt lgkmcnt(1)
	v_mfma_f32_16x16x32_bf16 v[64:67], v[204:207], v[128:131], v[80:83]
	v_mfma_f32_16x16x32_bf16 v[64:67], v[208:211], v[72:75], v[64:67]
	v_add_u32_e32 v2, 0x1800, v124
	s_waitcnt lgkmcnt(1)
	v_mfma_f32_16x16x32_bf16 v[68:71], v[212:215], v[128:131], v[84:87]
	v_mfma_f32_16x16x32_bf16 v[68:71], v[216:219], v[72:75], v[68:71]
	s_waitcnt lgkmcnt(0)
	v_mfma_f32_16x16x32_bf16 v[76:79], v[220:223], v[128:131], v[88:91]
	v_mfma_f32_16x16x32_bf16 v[72:75], v[224:227], v[72:75], v[76:79]
	s_andn2_b64 vcc, exec, s[8:9]
	s_cbranch_vccnz .LBB0_1007
